# out-proj residual epilogue pipelined the same way as FF2 (gate once, loads batched)
# speedup vs baseline: 1.0211x; 1.0095x over previous
; #define PG8_STAGE(bufoff, gbase, voff) do { _Pragma("unroll") for (int _i = 0; _i < 2; ++_i) \
;         __builtin_amdgcn_global_load_lds((const unsigned*)((const char*)(gbase) + (voff)[_i]), (LAS unsigned*)(lds + (bufoff) + ldsw + _i * 8192), 16, 0, 0); } while (0)
; #define PG8_WAIT_V(n) asm volatile("s_waitcnt vmcnt(" #n ")" ::: "memory")
; #define PG8_BAR __builtin_amdgcn_s_barrier()
;     __host__ __device__ bool next(int i, Unit& u) const {
;         const long L = (long)i * G + c; if (L >= nwg) return false;
;         int wgid = (int)L; { const int q = nwg / NXCD, r = nwg % NXCD, xcd = wgid % NXCD, off = wgid / NXCD; wgid = (xcd < r ? xcd * (q + 1) : r * (q + 1) + (xcd - r) * q) + off; }
;         const int nig = wgm * nN, gid = wgid / nig, fm = gid * wgm, gsz = (nM - fm) < wgm ? (nM - fm) : wgm;
;         u.pm = fm + ((wgid % nig) % gsz); u.pn = (wgid % nig) / gsz; return true;
; template <class Epi, class Sched>
; __device__ __forceinline__ void gemm_phase(LAS unsigned char* lds, const Gemm g, const Sched& S, const Epi& E) {
;     ...
;     const int aoff = lds_byte(wr * 64 + fr, fq * 8), boff = lds_byte(wc * 32 + fr, fq * 8);
;     ...
;     Unit cur, nxt; int ui = 0;
;     if (!S.next(0, cur)) return;
;     f32x4 acc[2][2][4][2];
; #pragma unroll
;     for (int a = 0; a < 2; ++a)
; #pragma unroll
;         for (int b = 0; b < 2; ++b)
; #pragma unroll
;             for (int m = 0; m < 4; ++m)
; #pragma unroll
;                 for (int n = 0; n < 2; ++n) acc[a][b][m][n] = (f32x4){0.f, 0.f, 0.f, 0.f};
;     bf16x8 At[4][2], B0[2][2], B1[2][2];
;     const char* cA = (const char*)g.A + (size_t)cur.pm * tstep; const char* cB = (const char*)g.Bt + (size_t)cur.pn * tstep;
;     S.a_ready(cur);
;     PG8_STAGE(PG8_SB(0, 0), cB, voffB); PG8_STAGE(PG8_SA(0, 0), cA, voffA); PG8_STAGE(PG8_SB(0, 1), cB + hstep, voffB); PG8_STAGE(PG8_SA(0, 1), cA + hstep, voffA);
;     if (wr == 1) PG8_BAR;
;     PG8_WAIT_V(4); PG8_BAR;
;     PG8_STAGE(PG8_SB(1, 0), cB + kstep, voffB); PG8_STAGE(PG8_SA(1, 0), cA + kstep, voffA); PG8_STAGE(PG8_SB(1, 1), cB + hstep + kstep, voffB);
;     PG8_WAIT_V(6); PG8_BAR;
.LBB0_1118:
	v_bfe_u32 v18, v2, 4, 2
	v_and_b32_e32 v150, 15, v2
	v_lshlrev_b32_e32 v19, 4, v18
	v_lshlrev_b32_e32 v2, 2, v2
	s_lshl_b32 s37, s0, 6
	v_lshl_or_b32 v19, v150, 6, v19
	s_lshl_b32 s0, s0, 13
	v_and_b32_e32 v2, 32, v2
	v_bitop3_b32 v20, v19, s0, v2 bitop3:0xde
	s_lshl_b32 s0, s1, 5
	s_and_b32 s3, s0, 0x60
	v_mov_b32_e32 v131, v1
	s_lshl_b32 s0, s3, 7
	v_lshl_add_u64 v[10:11], s[20:21], 0, v[130:131]
	v_mov_b32_e32 v133, v1
	v_bitop3_b32 v151, v19, s0, v2 bitop3:0xde
	s_mov_b64 s[0:1], 0x80
	v_lshl_add_u64 v[12:13], s[20:21], 0, v[132:133]
	s_add_i32 m0, s31, 0x18000
	v_lshl_add_u64 v[10:11], v[10:11], 0, s[0:1]
	v_lshl_add_u64 v[14:15], s[18:19], 0, v[130:131]
	s_waitcnt vmcnt(4)
	s_barrier
	global_load_lds_dwordx4 v[10:11], off
	v_lshl_add_u64 v[10:11], v[12:13], 0, s[0:1]
	s_add_i32 m0, s31, 0x1a000
	s_add_i32 s38, s31, 0x8000
	v_lshl_add_u64 v[16:17], s[18:19], 0, v[132:133]
	global_load_lds_dwordx4 v[10:11], off
	v_lshl_add_u64 v[10:11], v[14:15], 0, s[0:1]
	s_mov_b32 m0, s38
	s_add_i32 s39, s31, 0xa000
	global_load_lds_dwordx4 v[10:11], off
	v_lshl_add_u64 v[10:11], v[16:17], 0, s[0:1]
	s_add_u32 s0, s20, 0x80080
	s_mov_b32 m0, s39
	s_addc_u32 s1, s21, 0
	global_load_lds_dwordx4 v[10:11], off
	s_add_i32 m0, s31, 0x1c000
	v_lshl_add_u64 v[10:11], s[0:1], 0, v[130:131]
	global_load_lds_dwordx4 v[10:11], off
	v_lshl_add_u64 v[10:11], s[0:1], 0, v[132:133]
	s_add_i32 m0, s31, 0x1e000
	v_lshlrev_b32_e32 v0, 14, v0
	global_load_lds_dwordx4 v[10:11], off
	v_and_b32_e32 v0, 0x7fff8000, v0
	v_lshl_add_u32 v0, v3, 11, v0
	v_or_b32_e32 v0, v0, v4
	v_add_lshl_u32 v0, v0, v5, 1
	s_mov_b64 s[0:1], 0x80080
	v_lshl_add_u64 v[134:135], v[0:1], 0, s[0:1]
	v_lshlrev_b32_e32 v0, 14, v6
	v_and_b32_e32 v0, 0x7fff8000, v0
	v_lshl_add_u32 v0, v7, 11, v0
	s_waitcnt vmcnt(6)
	v_or_b32_e32 v0, v0, v8
	v_add_lshl_u32 v0, v0, v9, 1
	v_lshl_or_b32 v152, v18, 2, s3
	v_lshl_add_u64 v[136:137], v[0:1], 0, s[0:1]
	s_mov_b32 s40, 0
	v_add_u32_e32 v153, 0, v20
	s_barrier
	s_branch .LBB0_1120
.LBB0_1120:
	v_readlane_b32 s44, v251, 0
	s_add_i32 s40, s40, 1
	v_readlane_b32 s1, v252, 34
	v_readlane_b32 s50, v251, 6
	s_mul_i32 s1, s40, s1
	s_mul_hi_u32 s3, s40, s50
	s_add_i32 s3, s3, s1
	s_mul_i32 s1, s40, s50
	v_readlane_b32 s4, v253, 24
	s_add_u32 s10, s1, s54
	v_readlane_b32 s1, v252, 33
	v_readlane_b32 s5, v253, 25
	s_addc_u32 s11, s3, s1
	v_readlane_b32 s45, v251, 1
	v_mov_b64_e32 v[2:3], s[4:5]
	v_cmp_ge_i64_e64 s[4:5], s[10:11], v[2:3]
	s_and_b64 vcc, exec, s[4:5]
	v_readlane_b32 s46, v251, 2
	v_readlane_b32 s47, v251, 3
	v_readlane_b32 s48, v251, 4
	v_readlane_b32 s49, v251, 5
	v_readlane_b32 s51, v251, 7
	s_cbranch_vccnz .LBB0_1122
	s_ashr_i32 s0, s10, 31
	s_lshr_b32 s0, s0, 29
	s_add_i32 s0, s10, s0
	s_ashr_i32 s1, s0, 3
	s_and_b32 s0, s0, -8
	s_sub_i32 s0, s10, s0
	s_lshr_b32 s3, s0, 31
	s_or_b32 s3, s26, s3
	s_mul_i32 s0, s3, s0
	s_add_i32 s0, s0, s1
	s_ashr_i32 s1, s0, 31
	s_lshr_b32 s1, s1, 28
	s_add_i32 s1, s0, s1
	s_ashr_i32 s3, s1, 4
	s_lshl_b32 s3, s3, 1
	s_sub_i32 s8, s26, s3
	s_min_i32 s8, s8, 2
	s_abs_i32 s9, s8
	v_cvt_f32_u32_e32 v0, s9
	s_sub_i32 s13, 0, s9
	s_and_b32 s1, s1, -16
	s_sub_i32 s1, s0, s1
	v_rcp_iflag_f32_e32 v0, v0
	s_abs_i32 s0, s1
	s_xor_b32 s12, s1, s8
	s_ashr_i32 s12, s12, 31
	v_mul_f32_e32 v0, 0x4f7ffffe, v0
	v_cvt_u32_f32_e32 v0, v0
	s_nop 0
	v_readfirstlane_b32 s15, v0
	s_mul_i32 s13, s13, s15
	s_mul_hi_u32 s13, s15, s13
	s_add_i32 s15, s15, s13
	s_mul_hi_u32 s13, s0, s15
	s_mul_i32 s15, s13, s9
	s_sub_i32 s0, s0, s15
	s_add_i32 s17, s13, 1
	s_sub_i32 s15, s0, s9
	s_cmp_ge_u32 s0, s9
	s_cselect_b32 s13, s17, s13
	s_cselect_b32 s0, s15, s0
	s_add_i32 s15, s13, 1
	s_cmp_ge_u32 s0, s9
	s_cselect_b32 s0, s15, s13
	s_xor_b32 s0, s0, s12
	s_sub_i32 s0, s0, s12
	s_mul_i32 s8, s0, s8
	s_sub_i32 s1, s1, s8
	s_add_i32 s8, s1, s3

; #define PG8_STAGE(bufoff, gbase, voff) do { _Pragma("unroll") for (int _i = 0; _i < 2; ++_i) \
;         __builtin_amdgcn_global_load_lds((const unsigned*)((const char*)(gbase) + (voff)[_i]), (LAS unsigned*)(lds + (bufoff) + ldsw + _i * 8192), 16, 0, 0); } while (0)
; #define PG8_LDA(dst, b, h) do { _Pragma("unroll") for (int m = 0; m < 4; ++m) _Pragma("unroll") for (int k = 0; k < 2; ++k) dst[m][k] = *(const LAS bf16x8*)(lds + PG8_SA(b, h) + aoff + m * 2048 + k * 1024); } while (0)
; #define PG8_LDB(dst, b, h) do { _Pragma("unroll") for (int n = 0; n < 2; ++n) _Pragma("unroll") for (int k = 0; k < 2; ++k) dst[n][k] = *(const LAS bf16x8*)(lds + PG8_SB(b, h) + boff + n * 2048 + k * 1024); } while (0)
; #define PG8_MMA(ai, bj, At, Bt) do { __builtin_amdgcn_s_setprio(1); _Pragma("unroll") for (int m = 0; m < 4; ++m) _Pragma("unroll") for (int n = 0; n < 2; ++n) _Pragma("unroll") for (int k = 0; k < 2; ++k) \
;         acc[ai][bj][m][n] = __builtin_amdgcn_mfma_f32_16x16x32_bf16(Bt[n][k], At[m][k], acc[ai][bj][m][n], 0, 0, 0); __builtin_amdgcn_s_setprio(0); } while (0)
; #define PG8_WAIT_L(n) asm volatile("s_waitcnt lgkmcnt(" #n ")" ::: "memory")
; #define PG8_BAR __builtin_amdgcn_s_barrier()
; #define PG8_SCHED __builtin_amdgcn_sched_barrier(0)
; template <class Epi, class Sched>
; __device__ __forceinline__ void gemm_phase(LAS unsigned char* lds, const Gemm g, const Sched& S, const Epi& E) {
;     ...
;             PG8_LDB(B0, 0, 0); PG8_SCHED; PG8_LDA(At, 0, 0); PG8_STAGE(PG8_SA(1, 1), a1 + hstep, voffA);
;             PG8_WAIT_L(8); PG8_BAR; PG8_WAIT_L(0); PG8_MMA(0, 0, At, B0); PG8_BAR; PG8_SCHED;
;             PG8_LDB(B1, 0, 1); PG8_STAGE(PG8_SB(0, 0), b2, voffB);
;             PG8_BAR; PG8_WAIT_L(0); PG8_MMA(0, 1, At, B1); PG8_BAR;
;             PG8_LDA(At, 0, 1); PG8_STAGE(PG8_SA(0, 0), a2, voffA);
;             PG8_BAR; PG8_WAIT_L(0); PG8_MMA(1, 0, At, B0); PG8_BAR; PG8_SCHED;
.LBB0_1123:
	s_nop 0
	v_add_u32_e32 v0, s44, v151
	ds_read_b128 v[138:141], v0
	ds_read_b128 v[142:145], v0 offset:1024
	ds_read_b128 v[146:149], v0 offset:2048
	ds_read_b128 v[154:157], v0 offset:3072
	s_add_u32 s20, s18, 0x100
	s_addc_u32 s21, s19, 0
	s_cmp_eq_u32 s42, 28
	s_cselect_b32 s25, s3, s21
	s_cselect_b32 s24, s9, s20
	s_cselect_b32 s23, s1, s41
	s_cselect_b32 s22, s15, s17
	v_lshl_add_u64 v[190:191], s[18:19], 0, v[134:135]
	s_add_i32 m0, s31, 0xc000
	ds_read_b128 v[158:161], v153
	ds_read_b128 v[162:165], v153 offset:1024
	ds_read_b128 v[166:169], v153 offset:2048
	ds_read_b128 v[170:173], v153 offset:3072
	ds_read_b128 v[174:177], v153 offset:4096
	ds_read_b128 v[178:181], v153 offset:5120
	ds_read_b128 v[182:185], v153 offset:6144
	ds_read_b128 v[186:189], v153 offset:7168
	global_load_lds_dwordx4 v[190:191], off
	v_lshl_add_u64 v[190:191], s[18:19], 0, v[136:137]
	s_add_i32 m0, s31, 0xe000
	s_nop 0
	global_load_lds_dwordx4 v[190:191], off
	s_waitcnt lgkmcnt(8)
	s_barrier
	s_waitcnt lgkmcnt(0)
	s_setprio 1
	s_waitcnt lgkmcnt(0)
	v_mfma_f32_16x16x32_bf16 v[126:129], v[138:141], v[158:161], v[126:129]
	v_mfma_f32_16x16x32_bf16 v[122:125], v[146:149], v[158:161], v[122:125]
	v_mfma_f32_16x16x32_bf16 v[110:113], v[138:141], v[166:169], v[110:113]
	v_mfma_f32_16x16x32_bf16 v[106:109], v[146:149], v[166:169], v[106:109]
	v_mfma_f32_16x16x32_bf16 v[94:97], v[138:141], v[174:177], v[94:97]
	v_mfma_f32_16x16x32_bf16 v[90:93], v[146:149], v[174:177], v[90:93]
	v_mfma_f32_16x16x32_bf16 v[78:81], v[138:141], v[182:185], v[78:81]
	v_mfma_f32_16x16x32_bf16 v[74:77], v[146:149], v[182:185], v[74:77]
	v_mfma_f32_16x16x32_bf16 v[126:129], v[142:145], v[162:165], v[126:129]
	v_mfma_f32_16x16x32_bf16 v[122:125], v[154:157], v[162:165], v[122:125]
	v_mfma_f32_16x16x32_bf16 v[110:113], v[142:145], v[170:173], v[110:113]
	v_mfma_f32_16x16x32_bf16 v[106:109], v[154:157], v[170:173], v[106:109]
	v_mfma_f32_16x16x32_bf16 v[94:97], v[142:145], v[178:181], v[94:97]
	v_mfma_f32_16x16x32_bf16 v[90:93], v[154:157], v[178:181], v[90:93]
	v_mfma_f32_16x16x32_bf16 v[78:81], v[142:145], v[186:189], v[78:81]
	v_mfma_f32_16x16x32_bf16 v[74:77], v[154:157], v[186:189], v[74:77]
	s_setprio 0
	s_barrier
	s_add_i32 s43, 0, 0x14000
	s_add_i32 s18, s44, s30
	v_add_u32_e32 v0, s43, v151
	v_lshl_add_u64 v[206:207], s[22:23], 0, v[130:131]
	s_mov_b32 m0, s18
	ds_read_b128 v[190:193], v0
	ds_read_b128 v[194:197], v0 offset:1024
	ds_read_b128 v[198:201], v0 offset:2048
	ds_read_b128 v[202:205], v0 offset:3072
	global_load_lds_dwordx4 v[206:207], off
	v_lshl_add_u64 v[208:209], s[22:23], 0, v[132:133]
	s_add_i32 m0, s18, 0x2000
	s_nop 0
	global_load_lds_dwordx4 v[208:209], off
	s_barrier
	s_waitcnt lgkmcnt(0)
	s_setprio 1
	s_waitcnt lgkmcnt(0)
	v_mfma_f32_16x16x32_bf16 v[118:121], v[190:193], v[158:161], v[118:121]
	v_mfma_f32_16x16x32_bf16 v[114:117], v[198:201], v[158:161], v[114:117]
	v_mfma_f32_16x16x32_bf16 v[102:105], v[190:193], v[166:169], v[102:105]
	v_mfma_f32_16x16x32_bf16 v[98:101], v[198:201], v[166:169], v[98:101]
	v_mfma_f32_16x16x32_bf16 v[86:89], v[190:193], v[174:177], v[86:89]
	v_mfma_f32_16x16x32_bf16 v[82:85], v[198:201], v[174:177], v[82:85]
	v_mfma_f32_16x16x32_bf16 v[70:73], v[190:193], v[182:185], v[70:73]
	v_mfma_f32_16x16x32_bf16 v[66:69], v[198:201], v[182:185], v[66:69]
	v_mfma_f32_16x16x32_bf16 v[118:121], v[194:197], v[162:165], v[118:121]
	v_mfma_f32_16x16x32_bf16 v[114:117], v[202:205], v[162:165], v[114:117]
	v_mfma_f32_16x16x32_bf16 v[102:105], v[194:197], v[170:173], v[102:105]
	v_mfma_f32_16x16x32_bf16 v[98:101], v[202:205], v[170:173], v[98:101]
	v_mfma_f32_16x16x32_bf16 v[86:89], v[194:197], v[178:181], v[86:89]
	v_mfma_f32_16x16x32_bf16 v[82:85], v[202:205], v[178:181], v[82:85]
	v_mfma_f32_16x16x32_bf16 v[70:73], v[194:197], v[186:189], v[70:73]
	v_mfma_f32_16x16x32_bf16 v[66:69], v[202:205], v[186:189], v[66:69]
	s_setprio 0
	s_mov_b32 m0, s31
	v_lshl_add_u64 v[210:211], s[24:25], 0, v[130:131]
	s_barrier
	ds_read_b128 v[158:161], v153 offset:16384
	ds_read_b128 v[162:165], v153 offset:17408
	ds_read_b128 v[166:169], v153 offset:18432
	ds_read_b128 v[170:173], v153 offset:19456
	ds_read_b128 v[174:177], v153 offset:20480
	ds_read_b128 v[178:181], v153 offset:21504
	ds_read_b128 v[182:185], v153 offset:22528
	ds_read_b128 v[186:189], v153 offset:23552
	global_load_lds_dwordx4 v[210:211], off
	v_lshl_add_u64 v[220:221], s[24:25], 0, v[132:133]
	s_mov_b32 m0, s34
	s_nop 0
	global_load_lds_dwordx4 v[220:221], off
	s_barrier
	s_waitcnt lgkmcnt(0)
	s_setprio 1
	s_waitcnt lgkmcnt(0)
	v_mfma_f32_16x16x32_bf16 v[62:65], v[138:141], v[158:161], v[62:65]
	v_mfma_f32_16x16x32_bf16 v[58:61], v[146:149], v[158:161], v[58:61]
	v_mfma_f32_16x16x32_bf16 v[46:49], v[138:141], v[166:169], v[46:49]
	v_mfma_f32_16x16x32_bf16 v[42:45], v[146:149], v[166:169], v[42:45]
	v_mfma_f32_16x16x32_bf16 v[30:33], v[138:141], v[174:177], v[30:33]
	v_mfma_f32_16x16x32_bf16 v[26:29], v[146:149], v[174:177], v[26:29]
	v_mfma_f32_16x16x32_bf16 v[14:17], v[138:141], v[182:185], v[14:17]
	v_mfma_f32_16x16x32_bf16 v[10:13], v[146:149], v[182:185], v[10:13]
	v_mfma_f32_16x16x32_bf16 v[62:65], v[142:145], v[162:165], v[62:65]
	v_mfma_f32_16x16x32_bf16 v[58:61], v[154:157], v[162:165], v[58:61]
	v_mfma_f32_16x16x32_bf16 v[46:49], v[142:145], v[170:173], v[46:49]
	v_mfma_f32_16x16x32_bf16 v[42:45], v[154:157], v[170:173], v[42:45]
	v_mfma_f32_16x16x32_bf16 v[30:33], v[142:145], v[178:181], v[30:33]
	v_mfma_f32_16x16x32_bf16 v[26:29], v[154:157], v[178:181], v[26:29]
	v_mfma_f32_16x16x32_bf16 v[14:17], v[142:145], v[186:189], v[14:17]
	v_mfma_f32_16x16x32_bf16 v[10:13], v[154:157], v[186:189], v[10:13]
	s_setprio 0
	s_barrier
; #define PG8_STAGE(bufoff, gbase, voff) do { _Pragma("unroll") for (int _i = 0; _i < 2; ++_i) \
;         __builtin_amdgcn_global_load_lds((const unsigned*)((const char*)(gbase) + (voff)[_i]), (LAS unsigned*)(lds + (bufoff) + ldsw + _i * 8192), 16, 0, 0); } while (0)
; #define PG8_LDA(dst, b, h) do { _Pragma("unroll") for (int m = 0; m < 4; ++m) _Pragma("unroll") for (int k = 0; k < 2; ++k) dst[m][k] = *(const LAS bf16x8*)(lds + PG8_SA(b, h) + aoff + m * 2048 + k * 1024); } while (0)
; #define PG8_LDB(dst, b, h) do { _Pragma("unroll") for (int n = 0; n < 2; ++n) _Pragma("unroll") for (int k = 0; k < 2; ++k) dst[n][k] = *(const LAS bf16x8*)(lds + PG8_SB(b, h) + boff + n * 2048 + k * 1024); } while (0)
; #define PG8_MMA(ai, bj, At, Bt) do { __builtin_amdgcn_s_setprio(1); _Pragma("unroll") for (int m = 0; m < 4; ++m) _Pragma("unroll") for (int n = 0; n < 2; ++n) _Pragma("unroll") for (int k = 0; k < 2; ++k) \
;         acc[ai][bj][m][n] = __builtin_amdgcn_mfma_f32_16x16x32_bf16(Bt[n][k], At[m][k], acc[ai][bj][m][n], 0, 0, 0); __builtin_amdgcn_s_setprio(0); } while (0)
; #define PG8_WAIT_V(n) asm volatile("s_waitcnt vmcnt(" #n ")" ::: "memory")
; #define PG8_WAIT_L(n) asm volatile("s_waitcnt lgkmcnt(" #n ")" ::: "memory")
; #define PG8_BAR __builtin_amdgcn_s_barrier()
; #define PG8_SCHED __builtin_amdgcn_sched_barrier(0)
; template <class Epi, class Sched>
; __device__ __forceinline__ void gemm_phase(LAS unsigned char* lds, const Gemm g, const Sched& S, const Epi& E) {
;     ...
;             PG8_STAGE(PG8_SB(0, 1), b2 + hstep, voffB);
;             PG8_WAIT_V(6); PG8_BAR; PG8_MMA(1, 1, At, B1); PG8_BAR;
;             PG8_LDB(B0, 1, 0); PG8_SCHED; PG8_LDA(At, 1, 0); PG8_STAGE(PG8_SA(0, 1), a2 + hstep, voffA);
;             PG8_WAIT_L(8); PG8_BAR; PG8_WAIT_L(0); PG8_MMA(0, 0, At, B0); PG8_BAR; PG8_SCHED;
;             PG8_LDB(B1, 1, 1); PG8_STAGE(PG8_SB(1, 0), b3, voffB);
;             PG8_BAR; PG8_WAIT_L(0); PG8_MMA(0, 1, At, B1); PG8_BAR;
;             PG8_LDA(At, 1, 1); PG8_STAGE(PG8_SA(1, 0), a3, voffA);
	s_add_u32 s18, s22, 0x80000
	s_addc_u32 s19, s23, 0
	s_add_i32 s43, s43, s30
	v_lshl_add_u64 v[138:139], s[18:19], 0, v[130:131]
	s_mov_b32 m0, s43
	s_nop 0
	global_load_lds_dwordx4 v[138:139], off
	v_lshl_add_u64 v[138:139], s[18:19], 0, v[132:133]
	s_add_i32 m0, s43, 0x2000
	s_nop 0
	global_load_lds_dwordx4 v[138:139], off
	s_waitcnt vmcnt(6)
	s_barrier
	s_setprio 1
	v_mfma_f32_16x16x32_bf16 v[54:57], v[190:193], v[158:161], v[54:57]
	v_mfma_f32_16x16x32_bf16 v[50:53], v[198:201], v[158:161], v[50:53]
	v_mfma_f32_16x16x32_bf16 v[38:41], v[190:193], v[166:169], v[38:41]
	v_mfma_f32_16x16x32_bf16 v[34:37], v[198:201], v[166:169], v[34:37]
	v_mfma_f32_16x16x32_bf16 v[22:25], v[190:193], v[174:177], v[22:25]
	v_mfma_f32_16x16x32_bf16 v[18:21], v[198:201], v[174:177], v[18:21]
	v_mfma_f32_16x16x32_bf16 v[6:9], v[190:193], v[182:185], v[6:9]
	v_mfma_f32_16x16x32_bf16 v[2:5], v[198:201], v[182:185], v[2:5]
	v_mfma_f32_16x16x32_bf16 v[54:57], v[194:197], v[162:165], v[54:57]
	v_mfma_f32_16x16x32_bf16 v[50:53], v[202:205], v[162:165], v[50:53]
	v_mfma_f32_16x16x32_bf16 v[38:41], v[194:197], v[170:173], v[38:41]
	v_mfma_f32_16x16x32_bf16 v[34:37], v[202:205], v[170:173], v[34:37]
	v_mfma_f32_16x16x32_bf16 v[22:25], v[194:197], v[178:181], v[22:25]
	v_mfma_f32_16x16x32_bf16 v[18:21], v[202:205], v[178:181], v[18:21]
	v_mfma_f32_16x16x32_bf16 v[6:9], v[194:197], v[186:189], v[6:9]
	v_mfma_f32_16x16x32_bf16 v[2:5], v[202:205], v[186:189], v[2:5]
	s_setprio 0
	s_add_i32 s43, 0, 0x18000
	v_add_u32_e32 v0, s43, v151
	s_barrier
	ds_read_b128 v[138:141], v0
	ds_read_b128 v[142:145], v0 offset:1024
	ds_read_b128 v[146:149], v0 offset:2048
	ds_read_b128 v[154:157], v0 offset:3072
	s_add_u32 s18, s24, 0x80000
	s_addc_u32 s19, s25, 0
	s_mov_b32 m0, s35
	v_lshl_add_u64 v[190:191], s[18:19], 0, v[130:131]
	ds_read_b128 v[158:161], v153 offset:32768
	ds_read_b128 v[162:165], v153 offset:33792
	ds_read_b128 v[166:169], v153 offset:34816
	ds_read_b128 v[170:173], v153 offset:35840
	ds_read_b128 v[174:177], v153 offset:36864
	ds_read_b128 v[178:181], v153 offset:37888
	ds_read_b128 v[182:185], v153 offset:38912
	ds_read_b128 v[186:189], v153 offset:39936
	global_load_lds_dwordx4 v[190:191], off
	v_lshl_add_u64 v[190:191], s[18:19], 0, v[132:133]
	s_mov_b32 m0, s36
	s_nop 0
	global_load_lds_dwordx4 v[190:191], off
	s_waitcnt lgkmcnt(8)
	s_barrier
	s_waitcnt lgkmcnt(0)
	s_setprio 1
	s_waitcnt lgkmcnt(0)
	v_mfma_f32_16x16x32_bf16 v[126:129], v[138:141], v[158:161], v[126:129]
	v_mfma_f32_16x16x32_bf16 v[122:125], v[146:149], v[158:161], v[122:125]
	v_mfma_f32_16x16x32_bf16 v[110:113], v[138:141], v[166:169], v[110:113]
	v_mfma_f32_16x16x32_bf16 v[106:109], v[146:149], v[166:169], v[106:109]
	v_mfma_f32_16x16x32_bf16 v[94:97], v[138:141], v[174:177], v[94:97]
	v_mfma_f32_16x16x32_bf16 v[90:93], v[146:149], v[174:177], v[90:93]
	v_mfma_f32_16x16x32_bf16 v[78:81], v[138:141], v[182:185], v[78:81]
	v_mfma_f32_16x16x32_bf16 v[74:77], v[146:149], v[182:185], v[74:77]
	v_mfma_f32_16x16x32_bf16 v[126:129], v[142:145], v[162:165], v[126:129]
	v_mfma_f32_16x16x32_bf16 v[122:125], v[154:157], v[162:165], v[122:125]
	v_mfma_f32_16x16x32_bf16 v[110:113], v[142:145], v[170:173], v[110:113]
	v_mfma_f32_16x16x32_bf16 v[106:109], v[154:157], v[170:173], v[106:109]
	v_mfma_f32_16x16x32_bf16 v[94:97], v[142:145], v[178:181], v[94:97]
	v_mfma_f32_16x16x32_bf16 v[90:93], v[154:157], v[178:181], v[90:93]
	v_mfma_f32_16x16x32_bf16 v[78:81], v[142:145], v[186:189], v[78:81]
	v_mfma_f32_16x16x32_bf16 v[74:77], v[154:157], v[186:189], v[74:77]
	s_setprio 0
	s_barrier
	s_add_i32 s24, 0, 0x1c000
	s_add_i32 s18, s43, s30
	v_add_u32_e32 v0, s24, v151
	v_lshl_add_u64 v[206:207], v[206:207], 0, s[46:47]
	s_mov_b32 m0, s18
	ds_read_b128 v[190:193], v0
	ds_read_b128 v[194:197], v0 offset:1024
	ds_read_b128 v[198:201], v0 offset:2048
	ds_read_b128 v[202:205], v0 offset:3072
	global_load_lds_dwordx4 v[206:207], off
	v_lshl_add_u64 v[206:207], v[208:209], 0, s[46:47]
	s_add_i32 m0, s18, 0x2000
	s_nop 0
	global_load_lds_dwordx4 v[206:207], off
	s_barrier
	s_waitcnt lgkmcnt(0)
	s_setprio 1
	s_waitcnt lgkmcnt(0)
	v_mfma_f32_16x16x32_bf16 v[118:121], v[190:193], v[158:161], v[118:121]
	v_mfma_f32_16x16x32_bf16 v[114:117], v[198:201], v[158:161], v[114:117]
	v_mfma_f32_16x16x32_bf16 v[102:105], v[190:193], v[166:169], v[102:105]
	v_mfma_f32_16x16x32_bf16 v[98:101], v[198:201], v[166:169], v[98:101]
	v_mfma_f32_16x16x32_bf16 v[86:89], v[190:193], v[174:177], v[86:89]
	v_mfma_f32_16x16x32_bf16 v[82:85], v[198:201], v[174:177], v[82:85]
	v_mfma_f32_16x16x32_bf16 v[70:73], v[190:193], v[182:185], v[70:73]
	v_mfma_f32_16x16x32_bf16 v[66:69], v[198:201], v[182:185], v[66:69]
	v_mfma_f32_16x16x32_bf16 v[118:121], v[194:197], v[162:165], v[118:121]
	v_mfma_f32_16x16x32_bf16 v[114:117], v[202:205], v[162:165], v[114:117]
	v_mfma_f32_16x16x32_bf16 v[102:105], v[194:197], v[170:173], v[102:105]
	v_mfma_f32_16x16x32_bf16 v[98:101], v[202:205], v[170:173], v[98:101]
	v_mfma_f32_16x16x32_bf16 v[86:89], v[194:197], v[178:181], v[86:89]
	v_mfma_f32_16x16x32_bf16 v[82:85], v[202:205], v[178:181], v[82:85]
	v_mfma_f32_16x16x32_bf16 v[70:73], v[194:197], v[186:189], v[70:73]
	v_mfma_f32_16x16x32_bf16 v[66:69], v[202:205], v[186:189], v[66:69]
	s_setprio 0
	s_mov_b32 m0, s38
	v_lshl_add_u64 v[206:207], v[210:211], 0, s[46:47]
	s_barrier
	ds_read_b128 v[158:161], v153 offset:49152
	ds_read_b128 v[162:165], v153 offset:50176
	ds_read_b128 v[166:169], v153 offset:51200
	ds_read_b128 v[170:173], v153 offset:52224
	ds_read_b128 v[174:177], v153 offset:53248
	ds_read_b128 v[178:181], v153 offset:54272
	ds_read_b128 v[182:185], v153 offset:55296
	ds_read_b128 v[186:189], v153 offset:56320
	global_load_lds_dwordx4 v[206:207], off
	v_lshl_add_u64 v[206:207], v[220:221], 0, s[46:47]
	s_mov_b32 m0, s39
	s_nop 0
	global_load_lds_dwordx4 v[206:207], off
	s_barrier
; #define PG8_STAGE(bufoff, gbase, voff) do { _Pragma("unroll") for (int _i = 0; _i < 2; ++_i) \
;         __builtin_amdgcn_global_load_lds((const unsigned*)((const char*)(gbase) + (voff)[_i]), (LAS unsigned*)(lds + (bufoff) + ldsw + _i * 8192), 16, 0, 0); } while (0)
; #define PG8_MMA(ai, bj, At, Bt) do { __builtin_amdgcn_s_setprio(1); _Pragma("unroll") for (int m = 0; m < 4; ++m) _Pragma("unroll") for (int n = 0; n < 2; ++n) _Pragma("unroll") for (int k = 0; k < 2; ++k) \
;         acc[ai][bj][m][n] = __builtin_amdgcn_mfma_f32_16x16x32_bf16(Bt[n][k], At[m][k], acc[ai][bj][m][n], 0, 0, 0); __builtin_amdgcn_s_setprio(0); } while (0)
; #define PG8_WAIT_V(n) asm volatile("s_waitcnt vmcnt(" #n ")" ::: "memory")
; #define PG8_WAIT_L(n) asm volatile("s_waitcnt lgkmcnt(" #n ")" ::: "memory")
; template <class Epi, class Sched>
; __device__ __forceinline__ void gemm_phase(LAS unsigned char* lds, const Gemm g, const Sched& S, const Epi& E) {
;     ...
;             PG8_BAR; PG8_WAIT_L(0); PG8_MMA(1, 0, At, B0); PG8_BAR; PG8_SCHED;
;             PG8_STAGE(PG8_SB(1, 1), b3 + hstep, voffB);
;             PG8_WAIT_V(6); PG8_BAR; PG8_MMA(1, 1, At, B1); PG8_BAR;
;         }
;         E(acc, cur, wr, wc, fr, fq); S.done(cur);
;         if (!has_next) break;
;     __device__ __forceinline__ void operator()(const f32x4 (&acc)[2][2][4][2], const pg8::Unit& u, int wr, int wc, int fr, int fq) const {
;         const int row0 = u.pm * 256 + wr * 64 + fr; const int col0 = u.pn * 256 + wc * 32 + 4 * fq;
; #pragma unroll
;         for (int ai = 0; ai < 2; ++ai)
; #pragma unroll
;             for (int m = 0; m < 4; ++m) { const int row = row0 + ai * 128 + m * 16;
;                 const float* ip; float* op; int b;
;                 if (row < ML_ROWS) { b = row >> 11; ip = xi + (size_t)row * D; op = xo + (size_t)row * D; }
;                 else { b = 8; ip = ci + (size_t)(row - ML_ROWS) * D; op = co + (size_t)(row - ML_ROWS) * D; }
;                 const float* gp = mod + (size_t)b * 12288 + slot * 2048;
; #pragma unroll
;                 for (int bj = 0; bj < 2; ++bj)
; #pragma unroll
;                     for (int n = 0; n < 2; ++n) { const int c = col0 + bj * 128 + n * 16;
;                         const f32x4 r = *(const f32x4*)(ip + c), g = *(const f32x4*)(gp + c);
;                         *(f32x4*)(op + c) = r + g * acc[ai][bj][m][n]; } }
	s_waitcnt lgkmcnt(0)
	s_setprio 1
	s_waitcnt lgkmcnt(0)
	v_mfma_f32_16x16x32_bf16 v[62:65], v[138:141], v[158:161], v[62:65]
	v_mfma_f32_16x16x32_bf16 v[58:61], v[146:149], v[158:161], v[58:61]
	v_mfma_f32_16x16x32_bf16 v[46:49], v[138:141], v[166:169], v[46:49]
	v_mfma_f32_16x16x32_bf16 v[42:45], v[146:149], v[166:169], v[42:45]
	v_mfma_f32_16x16x32_bf16 v[30:33], v[138:141], v[174:177], v[30:33]
	v_mfma_f32_16x16x32_bf16 v[26:29], v[146:149], v[174:177], v[26:29]
	v_mfma_f32_16x16x32_bf16 v[14:17], v[138:141], v[182:185], v[14:17]
	v_mfma_f32_16x16x32_bf16 v[10:13], v[146:149], v[182:185], v[10:13]
	v_mfma_f32_16x16x32_bf16 v[62:65], v[142:145], v[162:165], v[62:65]
	v_mfma_f32_16x16x32_bf16 v[58:61], v[154:157], v[162:165], v[58:61]
	v_mfma_f32_16x16x32_bf16 v[46:49], v[142:145], v[170:173], v[46:49]
	v_mfma_f32_16x16x32_bf16 v[42:45], v[154:157], v[170:173], v[42:45]
	v_mfma_f32_16x16x32_bf16 v[30:33], v[142:145], v[178:181], v[30:33]
	v_mfma_f32_16x16x32_bf16 v[26:29], v[154:157], v[178:181], v[26:29]
	v_mfma_f32_16x16x32_bf16 v[14:17], v[142:145], v[186:189], v[14:17]
	v_mfma_f32_16x16x32_bf16 v[10:13], v[154:157], v[186:189], v[10:13]
	s_setprio 0
	s_barrier
	s_add_u32 s18, s22, 0x80080
	s_addc_u32 s19, s23, 0
	s_add_i32 s22, s24, s30
	v_lshl_add_u64 v[138:139], s[18:19], 0, v[130:131]
	s_mov_b32 m0, s22
	s_nop 0
	global_load_lds_dwordx4 v[138:139], off
	v_lshl_add_u64 v[138:139], s[18:19], 0, v[132:133]
	s_add_i32 m0, s22, 0x2000
	s_nop 0
	global_load_lds_dwordx4 v[138:139], off
	s_waitcnt vmcnt(6)
	s_barrier
	s_setprio 1
	v_mfma_f32_16x16x32_bf16 v[54:57], v[190:193], v[158:161], v[54:57]
	v_mfma_f32_16x16x32_bf16 v[50:53], v[198:201], v[158:161], v[50:53]
	v_mfma_f32_16x16x32_bf16 v[38:41], v[190:193], v[166:169], v[38:41]
	v_mfma_f32_16x16x32_bf16 v[34:37], v[198:201], v[166:169], v[34:37]
	v_mfma_f32_16x16x32_bf16 v[22:25], v[190:193], v[174:177], v[22:25]
	v_mfma_f32_16x16x32_bf16 v[18:21], v[198:201], v[174:177], v[18:21]
	v_mfma_f32_16x16x32_bf16 v[6:9], v[190:193], v[182:185], v[6:9]
	v_mfma_f32_16x16x32_bf16 v[2:5], v[198:201], v[182:185], v[2:5]
	v_mfma_f32_16x16x32_bf16 v[54:57], v[194:197], v[162:165], v[54:57]
	v_mfma_f32_16x16x32_bf16 v[50:53], v[202:205], v[162:165], v[50:53]
	v_mfma_f32_16x16x32_bf16 v[38:41], v[194:197], v[170:173], v[38:41]
	v_mfma_f32_16x16x32_bf16 v[34:37], v[202:205], v[170:173], v[34:37]
	v_mfma_f32_16x16x32_bf16 v[22:25], v[194:197], v[178:181], v[22:25]
	v_mfma_f32_16x16x32_bf16 v[18:21], v[202:205], v[178:181], v[18:21]
	v_mfma_f32_16x16x32_bf16 v[6:9], v[194:197], v[186:189], v[6:9]
	v_mfma_f32_16x16x32_bf16 v[2:5], v[202:205], v[186:189], v[2:5]
	s_setprio 0
	s_add_i32 s42, s42, 2
	s_add_u32 s17, s17, 0x100
	s_addc_u32 s41, s41, 0
	s_cmp_gt_u32 s42, 29
	s_mov_b64 s[18:19], s[20:21]
	s_barrier
	s_cbranch_scc0 .LBB0_1123
	s_lshl_b32 s1, s16, 8
	s_add_i32 s1, s1, s37
	v_readlane_b32 s44, v251, 0
	v_readlane_b32 s45, v251, 1
	v_readlane_b32 s46, v251, 2
	v_readlane_b32 s47, v251, 3
	v_readlane_b32 s48, v251, 4
	v_readlane_b32 s49, v251, 5
	v_readlane_b32 s50, v251, 6
	v_readlane_b32 s51, v251, 7
	v_readlane_b32 s22, v254, 4
	v_readlane_b32 s23, v254, 5
	v_readlane_b32 s20, v254, 6
	v_readlane_b32 s21, v254, 7
	v_readlane_b32 s18, v254, 2
	v_readlane_b32 s19, v254, 3
	s_add_i32 s3, s1, 0xffffc000
	s_ashr_i32 s15, s1, 11
	s_cmpk_lt_i32 s1, 0x4000
	s_cselect_b32 s22, s22, s20
	s_cselect_b32 s23, s23, s21
	s_cselect_b32 s20, s46, s60
	s_cselect_b32 s21, s47, s61
	s_cselect_b32 s3, s1, s3
	s_cselect_b32 s15, s15, 8
	s_mul_i32 s15, s15, 0xc000
	s_add_u32 s18, s18, s15
	s_addc_u32 s19, s19, 0
	s_add_u32 s18, s18, 0x4000
	s_addc_u32 s19, s19, 0
	v_add_u32_e32 v138, s3, v150
	v_lshl_or_b32 v139, s14, 8, v152
	v_lshlrev_b32_e32 v139, 2, v139
	v_lshl_or_b32 v138, v138, 13, v139
	v_add_u32_e32 v140, 0x20000, v138
	v_add_u32_e32 v141, 0x40000, v138
	v_add_u32_e32 v0, 0x60000, v138
	v_add_u32_e32 v210, 0x100000, v138
	v_add_u32_e32 v211, 0x120000, v138
	v_add_u32_e32 v220, 0x140000, v138
	global_load_dwordx4 v[154:157], v139, s[18:19]
	global_load_dwordx4 v[158:161], v139, s[18:19] offset:64
	global_load_dwordx4 v[162:165], v139, s[18:19] offset:512
	global_load_dwordx4 v[166:169], v139, s[18:19] offset:576
	v_add_u32_e32 v139, 0x160000, v138
	global_load_dwordx4 v[170:173], v138, s[22:23]
	global_load_dwordx4 v[174:177], v138, s[22:23] offset:64
	global_load_dwordx4 v[178:181], v138, s[22:23] offset:512
	global_load_dwordx4 v[182:185], v138, s[22:23] offset:576
	global_load_dwordx4 v[186:189], v140, s[22:23]
	global_load_dwordx4 v[190:193], v140, s[22:23] offset:64
	global_load_dwordx4 v[194:197], v140, s[22:23] offset:512
	global_load_dwordx4 v[198:201], v140, s[22:23] offset:576
	global_load_dwordx4 v[202:205], v141, s[22:23]
	global_load_dwordx4 v[206:209], v141, s[22:23] offset:64
	global_load_dwordx4 v[142:145], v141, s[22:23] offset:512
	global_load_dwordx4 v[146:149], v141, s[22:23] offset:576
	s_waitcnt vmcnt(8)
	v_pk_fma_f32 v[126:127], v[126:127], v[154:155], v[170:171]
	v_pk_fma_f32 v[128:129], v[128:129], v[156:157], v[172:173]
	v_pk_fma_f32 v[122:123], v[122:123], v[158:159], v[174:175]
	v_pk_fma_f32 v[124:125], v[124:125], v[160:161], v[176:177]
	v_pk_fma_f32 v[118:119], v[118:119], v[162:163], v[178:179]
	v_pk_fma_f32 v[120:121], v[120:121], v[164:165], v[180:181]
	v_pk_fma_f32 v[114:115], v[114:115], v[166:167], v[182:183]
	v_pk_fma_f32 v[116:117], v[116:117], v[168:169], v[184:185]
	global_store_dwordx4 v138, v[126:129], s[20:21]
	global_store_dwordx4 v138, v[122:125], s[20:21] offset:64
	global_store_dwordx4 v138, v[118:121], s[20:21] offset:512
	global_store_dwordx4 v138, v[114:117], s[20:21] offset:576
	global_load_dwordx4 v[170:173], v0, s[22:23]
	global_load_dwordx4 v[174:177], v0, s[22:23] offset:64
	global_load_dwordx4 v[178:181], v0, s[22:23] offset:512
	global_load_dwordx4 v[182:185], v0, s[22:23] offset:576
	s_waitcnt vmcnt(12)
; template <class Epi, class Sched>
; __device__ __forceinline__ void gemm_phase(LAS unsigned char* lds, const Gemm g, const Sched& S, const Epi& E) {
;     ...
;         E(acc, cur, wr, wc, fr, fq); S.done(cur);
;         if (!has_next) break;
; #pragma unroll
;         for (int a = 0; a < 2; ++a)
; #pragma unroll
;             for (int b = 0; b < 2; ++b)
; #pragma unroll
;                 for (int m = 0; m < 4; ++m)
; #pragma unroll
;                     for (int n = 0; n < 2; ++n) acc[a][b][m][n] = (f32x4){0.f, 0.f, 0.f, 0.f};
;         cur = nxt; cA = nA; cB = nB; ++ui;
;     __device__ __forceinline__ void operator()(const f32x4 (&acc)[2][2][4][2], const pg8::Unit& u, int wr, int wc, int fr, int fq) const {
;     ...
;         for (int ai = 0; ai < 2; ++ai)
; #pragma unroll
;             for (int m = 0; m < 4; ++m) { const int row = row0 + ai * 128 + m * 16;
;                 const float* ip; float* op; int b;
;                 if (row < ML_ROWS) { b = row >> 11; ip = xi + (size_t)row * D; op = xo + (size_t)row * D; }
;                 else { b = 8; ip = ci + (size_t)(row - ML_ROWS) * D; op = co + (size_t)(row - ML_ROWS) * D; }
;                 const float* gp = mod + (size_t)b * 12288 + slot * 2048;
; #pragma unroll
;                 for (int bj = 0; bj < 2; ++bj)
; #pragma unroll
;                     for (int n = 0; n < 2; ++n) { const int c = col0 + bj * 128 + n * 16;
;                         const f32x4 r = *(const f32x4*)(ip + c), g = *(const f32x4*)(gp + c);
;                         *(f32x4*)(op + c) = r + g * acc[ai][bj][m][n]; } }
	v_pk_fma_f32 v[110:111], v[110:111], v[154:155], v[186:187]
	v_pk_fma_f32 v[112:113], v[112:113], v[156:157], v[188:189]
	v_pk_fma_f32 v[106:107], v[106:107], v[158:159], v[190:191]
	v_pk_fma_f32 v[108:109], v[108:109], v[160:161], v[192:193]
	v_pk_fma_f32 v[102:103], v[102:103], v[162:163], v[194:195]
	v_pk_fma_f32 v[104:105], v[104:105], v[164:165], v[196:197]
	v_pk_fma_f32 v[98:99], v[98:99], v[166:167], v[198:199]
	v_pk_fma_f32 v[100:101], v[100:101], v[168:169], v[200:201]
	global_store_dwordx4 v140, v[110:113], s[20:21]
	global_store_dwordx4 v140, v[106:109], s[20:21] offset:64
	global_store_dwordx4 v140, v[102:105], s[20:21] offset:512
	global_store_dwordx4 v140, v[98:101], s[20:21] offset:576
	global_load_dwordx4 v[186:189], v210, s[22:23]
	global_load_dwordx4 v[190:193], v210, s[22:23] offset:64
	global_load_dwordx4 v[194:197], v210, s[22:23] offset:512
	global_load_dwordx4 v[198:201], v210, s[22:23] offset:576
	s_waitcnt vmcnt(16)
	v_pk_fma_f32 v[94:95], v[94:95], v[154:155], v[202:203]
	v_pk_fma_f32 v[96:97], v[96:97], v[156:157], v[204:205]
	v_pk_fma_f32 v[90:91], v[90:91], v[158:159], v[206:207]
	v_pk_fma_f32 v[92:93], v[92:93], v[160:161], v[208:209]
	v_pk_fma_f32 v[86:87], v[86:87], v[162:163], v[142:143]
	v_pk_fma_f32 v[88:89], v[88:89], v[164:165], v[144:145]
	v_pk_fma_f32 v[82:83], v[82:83], v[166:167], v[146:147]
	v_pk_fma_f32 v[84:85], v[84:85], v[168:169], v[148:149]
	global_store_dwordx4 v141, v[94:97], s[20:21]
	global_store_dwordx4 v141, v[90:93], s[20:21] offset:64
	global_store_dwordx4 v141, v[86:89], s[20:21] offset:512
	global_store_dwordx4 v141, v[82:85], s[20:21] offset:576
	global_load_dwordx4 v[202:205], v211, s[22:23]
	global_load_dwordx4 v[206:209], v211, s[22:23] offset:64
	global_load_dwordx4 v[142:145], v211, s[22:23] offset:512
	global_load_dwordx4 v[146:149], v211, s[22:23] offset:576
	s_waitcnt vmcnt(16)
	v_pk_fma_f32 v[78:79], v[78:79], v[154:155], v[170:171]
	v_pk_fma_f32 v[80:81], v[80:81], v[156:157], v[172:173]
	v_pk_fma_f32 v[74:75], v[74:75], v[158:159], v[174:175]
	v_pk_fma_f32 v[76:77], v[76:77], v[160:161], v[176:177]
	v_pk_fma_f32 v[70:71], v[70:71], v[162:163], v[178:179]
	v_pk_fma_f32 v[72:73], v[72:73], v[164:165], v[180:181]
	v_pk_fma_f32 v[66:67], v[66:67], v[166:167], v[182:183]
	v_pk_fma_f32 v[68:69], v[68:69], v[168:169], v[184:185]
	global_store_dwordx4 v0, v[78:81], s[20:21]
	global_store_dwordx4 v0, v[74:77], s[20:21] offset:64
	global_store_dwordx4 v0, v[70:73], s[20:21] offset:512
	global_store_dwordx4 v0, v[66:69], s[20:21] offset:576
	global_load_dwordx4 v[170:173], v220, s[22:23]
	global_load_dwordx4 v[174:177], v220, s[22:23] offset:64
	global_load_dwordx4 v[178:181], v220, s[22:23] offset:512
	global_load_dwordx4 v[182:185], v220, s[22:23] offset:576
	s_waitcnt vmcnt(16)
	v_pk_fma_f32 v[62:63], v[62:63], v[154:155], v[186:187]
	v_pk_fma_f32 v[64:65], v[64:65], v[156:157], v[188:189]
	v_pk_fma_f32 v[58:59], v[58:59], v[158:159], v[190:191]
	v_pk_fma_f32 v[60:61], v[60:61], v[160:161], v[192:193]
	v_pk_fma_f32 v[54:55], v[54:55], v[162:163], v[194:195]
	v_pk_fma_f32 v[56:57], v[56:57], v[164:165], v[196:197]
	v_pk_fma_f32 v[50:51], v[50:51], v[166:167], v[198:199]
	v_pk_fma_f32 v[52:53], v[52:53], v[168:169], v[200:201]
	global_store_dwordx4 v210, v[62:65], s[20:21]
	global_store_dwordx4 v210, v[58:61], s[20:21] offset:64
	global_store_dwordx4 v210, v[54:57], s[20:21] offset:512
	global_store_dwordx4 v210, v[50:53], s[20:21] offset:576
	global_load_dwordx4 v[186:189], v139, s[22:23]
	global_load_dwordx4 v[190:193], v139, s[22:23] offset:64
	global_load_dwordx4 v[194:197], v139, s[22:23] offset:512
	global_load_dwordx4 v[198:201], v139, s[22:23] offset:576
	s_waitcnt vmcnt(16)
	v_pk_fma_f32 v[46:47], v[46:47], v[154:155], v[202:203]
	v_pk_fma_f32 v[48:49], v[48:49], v[156:157], v[204:205]
	v_pk_fma_f32 v[42:43], v[42:43], v[158:159], v[206:207]
	v_pk_fma_f32 v[44:45], v[44:45], v[160:161], v[208:209]
	v_pk_fma_f32 v[38:39], v[38:39], v[162:163], v[142:143]
	v_pk_fma_f32 v[40:41], v[40:41], v[164:165], v[144:145]
	v_pk_fma_f32 v[34:35], v[34:35], v[166:167], v[146:147]
	v_pk_fma_f32 v[36:37], v[36:37], v[168:169], v[148:149]
	global_store_dwordx4 v211, v[46:49], s[20:21]
	global_store_dwordx4 v211, v[42:45], s[20:21] offset:64
	global_store_dwordx4 v211, v[38:41], s[20:21] offset:512
	global_store_dwordx4 v211, v[34:37], s[20:21] offset:576
	s_waitcnt vmcnt(12)
	v_pk_fma_f32 v[30:31], v[30:31], v[154:155], v[170:171]
	v_pk_fma_f32 v[32:33], v[32:33], v[156:157], v[172:173]
	v_pk_fma_f32 v[26:27], v[26:27], v[158:159], v[174:175]
	v_pk_fma_f32 v[28:29], v[28:29], v[160:161], v[176:177]
	v_pk_fma_f32 v[22:23], v[22:23], v[162:163], v[178:179]
	v_pk_fma_f32 v[24:25], v[24:25], v[164:165], v[180:181]
	v_pk_fma_f32 v[18:19], v[18:19], v[166:167], v[182:183]
	v_pk_fma_f32 v[20:21], v[20:21], v[168:169], v[184:185]
	global_store_dwordx4 v220, v[30:33], s[20:21]
	global_store_dwordx4 v220, v[26:29], s[20:21] offset:64
	global_store_dwordx4 v220, v[22:25], s[20:21] offset:512
	global_store_dwordx4 v220, v[18:21], s[20:21] offset:576
	s_waitcnt vmcnt(8)
	v_pk_fma_f32 v[14:15], v[14:15], v[154:155], v[186:187]
	v_pk_fma_f32 v[16:17], v[16:17], v[156:157], v[188:189]
	v_pk_fma_f32 v[10:11], v[10:11], v[158:159], v[190:191]
	v_pk_fma_f32 v[12:13], v[12:13], v[160:161], v[192:193]
	v_pk_fma_f32 v[6:7], v[6:7], v[162:163], v[194:195]
	v_pk_fma_f32 v[8:9], v[8:9], v[164:165], v[196:197]
	v_pk_fma_f32 v[2:3], v[2:3], v[166:167], v[198:199]
	v_pk_fma_f32 v[4:5], v[4:5], v[168:169], v[200:201]
	global_store_dwordx4 v139, v[14:17], s[20:21]
	global_store_dwordx4 v139, v[10:13], s[20:21] offset:64
	global_store_dwordx4 v139, v[6:9], s[20:21] offset:512
	global_store_dwordx4 v139, v[2:5], s[20:21] offset:576
	v_mov_b32_e32 v170, v219
	s_mov_b32 s14, s0
	s_mov_b32 s16, s8
	s_mov_b64 s[20:21], s[12:13]
	s_mov_b64 s[18:19], s[10:11]
	s_and_b64 vcc, exec, s[4:5]
	s_cbranch_vccnz .LBB0_1156
	s_branch .LBB0_1120
